# FFN-up GEMM: per-tile row sum-of-squares records prefetched to LDS by one LDS-DMA load ahead of the K loop; epilogue reads them from LDS
# speedup vs baseline: 1.0200x; 1.0132x over previous
; template <class Epi>
; __device__ __forceinline__ void gemm_phase(LAS unsigned char* lds, const Gemm g, const Epi& E) {
;     ...
; #pragma unroll
;         for (int a = 0; a < 2; ++a)
; #pragma unroll
;             for (int b = 0; b < 2; ++b)
; #pragma unroll
;                 for (int m = 0; m < 4; ++m)
; #pragma unroll
;                     for (int n = 0; n < 2; ++n) acc[a][b][m][n] = (f32x4){0.f, 0.f, 0.f, 0.f};
;         cur = nxt; cA = nA; cB = nB; ++ui;
;     __device__ __forceinline__ void operator()(AccRef acc, const Unit& u, int wr, int wc, int fr, int fq) const {
;     ...
;                 const float rs = rsqrtf(ssq_sum<4>(ssqx + (size_t)(row0 + ai * 128 + m * 16) * 4) * (1.0f / DM) + EPS);
.LBB0_790:
	s_andn2_b64 vcc, exec, s[10:11]
	s_cbranch_vccnz .LBB0_793
	s_cmp_lg_u32 s54, 1
	s_cbranch_scc1 .Lup_ssq_skip
	v_lshl_add_u32 v144, s21, 8, v208
	v_mov_b32_e32 v145, 0
	v_subrev_u32_e32 v144, 0x100, v144
	v_readfirstlane_b32 s46, v208
	v_lshl_add_u64 v[144:145], v[144:145], 4, s[56:57]
	s_nop 1
	s_lshl_b32 s46, s46, 4
	s_add_i32 s46, s46, 0x20400
	s_mov_b32 m0, s46
	s_nop 0
	global_load_lds_dwordx4 v[144:145], off
.Lup_ssq_skip:
	s_add_u32 s46, s50, 0x80
	s_addc_u32 s47, s51, 0
	s_add_u32 s24, s48, 0x100
	s_addc_u32 s25, s49, 0
	s_mov_b32 s48, 0
	v_mov_b64_e32 v[2:3], 0
	v_mov_b64_e32 v[4:5], 0
	v_mov_b64_e32 v[6:7], 0
	v_mov_b64_e32 v[8:9], 0
	v_mov_b64_e32 v[10:11], 0
	v_mov_b64_e32 v[12:13], 0
	v_mov_b64_e32 v[14:15], 0
	v_mov_b64_e32 v[16:17], 0
	v_mov_b64_e32 v[18:19], 0
	v_mov_b64_e32 v[20:21], 0
	v_mov_b64_e32 v[22:23], 0
	v_mov_b64_e32 v[24:25], 0
	v_mov_b64_e32 v[26:27], 0
	v_mov_b64_e32 v[28:29], 0
	v_mov_b64_e32 v[30:31], 0
	v_mov_b64_e32 v[32:33], 0
	v_mov_b64_e32 v[34:35], 0
	v_mov_b64_e32 v[36:37], 0
	v_mov_b64_e32 v[38:39], 0
	v_mov_b64_e32 v[40:41], 0
	v_mov_b64_e32 v[42:43], 0
	v_mov_b64_e32 v[44:45], 0
	v_mov_b64_e32 v[46:47], 0
	v_mov_b64_e32 v[48:49], 0
	v_mov_b64_e32 v[50:51], 0
	v_mov_b64_e32 v[52:53], 0
	v_mov_b64_e32 v[54:55], 0
	v_mov_b64_e32 v[56:57], 0
	v_mov_b64_e32 v[58:59], 0
	v_mov_b64_e32 v[60:61], 0
	v_mov_b64_e32 v[62:63], 0
	v_mov_b64_e32 v[64:65], 0
	v_mov_b64_e32 v[66:67], 0
	v_mov_b64_e32 v[68:69], 0
	v_mov_b64_e32 v[70:71], 0
	v_mov_b64_e32 v[72:73], 0
	v_mov_b64_e32 v[74:75], 0
	v_mov_b64_e32 v[76:77], 0
	v_mov_b64_e32 v[78:79], 0
	v_mov_b64_e32 v[80:81], 0
	v_mov_b64_e32 v[82:83], 0
	v_mov_b64_e32 v[84:85], 0
	v_mov_b64_e32 v[86:87], 0
	v_mov_b64_e32 v[88:89], 0
	v_mov_b64_e32 v[90:91], 0
	v_mov_b64_e32 v[92:93], 0
	v_mov_b64_e32 v[94:95], 0
	v_mov_b64_e32 v[96:97], 0
	v_mov_b64_e32 v[98:99], 0
	v_mov_b64_e32 v[100:101], 0
	v_mov_b64_e32 v[102:103], 0
	v_mov_b64_e32 v[104:105], 0
	v_mov_b64_e32 v[106:107], 0
	v_mov_b64_e32 v[108:109], 0
	v_mov_b64_e32 v[110:111], 0
	v_mov_b64_e32 v[112:113], 0
	v_mov_b64_e32 v[114:115], 0
	v_mov_b64_e32 v[116:117], 0
	v_mov_b64_e32 v[118:119], 0
	v_mov_b64_e32 v[120:121], 0
	v_mov_b64_e32 v[122:123], 0
	v_mov_b64_e32 v[124:125], 0
	v_mov_b64_e32 v[126:127], 0
	v_mov_b64_e32 v[128:129], 0

; __device__ __forceinline__ unsigned cvtpk(float lo, float hi) { f32x2 v = {lo, hi}; bf16x2_t b = __builtin_convertvector(v, bf16x2_t); return __builtin_bit_cast(unsigned, b); }
;     __device__ __forceinline__ void operator()(AccRef acc, const Unit& u, int wr, int wc, int fr, int fq) const {
;         const int row0 = u.pm * 256 + wr * 64 + fr, gcol = u.pn * 128 + wc * 32 + 8 * fq;
; #pragma unroll
;         for (int ai = 0; ai < 2; ++ai) {
; #pragma unroll
;             for (int m = 0; m < 4; ++m) {
;                 const float rs = rsqrtf(ssq_sum<4>(ssqx + (size_t)(row0 + ai * 128 + m * 16) * 4) * (1.0f / DM) + EPS);
; #pragma unroll
;                 for (int bj = 0; bj < 2; ++bj) { acc[ai][bj][m][0] = acc[ai][bj][m][0] * rs; acc[ai][bj][m][1] = acc[ai][bj][m][1] * rs; }
;             }
;             asm volatile("" ::: "memory");
;             const int chunk = u.pm * 4 + ai * 2 + wr;
; #pragma unroll
;             for (int e = 0; e < 2; ++e) {
;                 const int m = e ? 3 : 0;
;                 const bool mine = e ? (fr >= 14) : (fr <= 1);
;                 const int slot = e ? (fr - 12) : fr;
;                 if (mine) {
; #pragma unroll
;                     for (int bj = 0; bj < 2; ++bj) {
;                         const f32x4 v0 = acc[ai][bj][m][0], v1 = acc[ai][bj][m][1];
;                         u32x4 w; w.x = cvtpk(v0[0], v0[1]); w.y = cvtpk(v0[2], v0[3]); w.z = cvtpk(v1[0], v1[1]); w.w = cvtpk(v1[2], v1[3]);
;                         *(u32x4*)(UB + ((size_t)chunk * 4 + slot) * NUP + bj * DFF + gcol) = w;
;                     }
;                 }
;             }
.LBB0_795:
	v_lshl_add_u32 v146, s21, 8, v137
	v_ashrrev_i32_e32 v147, 31, v146
	v_and_b32_e32 v148, 0xff, v146
	v_lshlrev_b32_e32 v148, 4, v148
	v_add_u32_e32 v148, 0x21400, v148
	ds_read_b128 v[148:151], v148
	s_mov_b32 s12, 0x3a800000
	v_lshl_or_b32 v144, s20, 7, v242
	s_lshl_b32 s20, s21, 2
	s_add_i32 s52, s20, s54
	s_ashr_i32 s53, s52, 31
	v_ashrrev_i32_e32 v145, 31, v144
	s_lshl_b64 s[50:51], s[52:53], 2
	s_waitcnt lgkmcnt(0)
	v_mov_b32_e32 v152, v149
	v_mov_b32_e32 v153, v150
	v_mov_b32_e32 v149, v151
	v_pk_add_f32 v[154:155], v[152:153], v[148:149]
	v_or_b32_e32 v148, 16, v146
	v_ashrrev_i32_e32 v149, 31, v148
	v_and_b32_e32 v150, 0xff, v148
	v_lshlrev_b32_e32 v150, 4, v150
	v_add_u32_e32 v150, 0x21400, v150
	ds_read_b128 v[150:153], v150
	s_waitcnt lgkmcnt(0)
	v_mov_b32_e32 v156, v151
	v_mov_b32_e32 v157, v152
	v_mov_b32_e32 v151, v153
	v_pk_add_f32 v[150:151], v[156:157], v[150:151]
	v_mov_b32_e32 v153, v154
	v_mov_b32_e32 v152, v150
	v_mov_b32_e32 v154, v151
	v_pk_add_f32 v[150:151], v[152:153], v[154:155]
	v_or_b32_e32 v152, 48, v146
	v_pk_add_f32 v[150:151], v[150:151], 0 op_sel_hi:[1,0]
	v_ashrrev_i32_e32 v153, 31, v152
	v_pk_fma_f32 v[180:181], v[150:151], s[12:13], v[212:213] op_sel_hi:[1,0,0]
	s_nop 0
	v_mul_f32_e32 v147, 0x4b800000, v181
	v_cmp_gt_f32_e32 vcc, s69, v181
	v_cmp_gt_f32_e64 s[46:47], s69, v180
	s_nop 0
	v_cndmask_b32_e32 v147, v181, v147, vcc
	v_rsq_f32_e32 v147, v147
	s_nop 0
	v_mul_f32_e32 v149, 0x45800000, v147
	v_cndmask_b32_e32 v150, v147, v149, vcc
	v_pk_mul_f32 v[158:159], v[124:125], v[150:151] op_sel_hi:[1,0]
	v_pk_mul_f32 v[182:183], v[122:123], v[150:151] op_sel_hi:[1,0]
	v_pk_mul_f32 v[122:123], v[128:129], v[150:151] op_sel_hi:[1,0]
	v_pk_mul_f32 v[126:127], v[126:127], v[150:151] op_sel_hi:[1,0]
	v_pk_mul_f32 v[160:161], v[120:121], v[150:151] op_sel_hi:[1,0]
	v_pk_mul_f32 v[184:185], v[118:119], v[150:151] op_sel_hi:[1,0]
	v_pk_mul_f32 v[124:125], v[116:117], v[150:151] op_sel_hi:[1,0]
	v_pk_mul_f32 v[128:129], v[114:115], v[150:151] op_sel_hi:[1,0]
	v_or_b32_e32 v150, 32, v146
	v_ashrrev_i32_e32 v151, 31, v150
	v_and_b32_e32 v114, 0xff, v150
	v_lshlrev_b32_e32 v114, 4, v114
	v_add_u32_e32 v114, 0x21400, v114
	v_and_b32_e32 v118, 0xff, v152
	v_lshlrev_b32_e32 v118, 4, v118
	v_add_u32_e32 v118, 0x21400, v118
	ds_read_b128 v[114:117], v114
	s_nop 0
	ds_read_b128 v[118:121], v118
	s_and_saveexec_b64 s[20:21], s[42:43]
	s_cbranch_execz .LBB0_797
	v_or_b32_e32 v147, s50, v136
	v_mov_b64_e32 v[162:163], s[94:95]
	s_movk_i32 s12, 0x2c00
	v_mad_u64_u32 v[162:163], s[24:25], v147, s12, v[162:163]
	v_mad_i32_i24 v163, s51, v240, v163
	v_cvt_pk_bf16_f32 v154, v182, v183
	v_cvt_pk_bf16_f32 v155, v158, v159
	v_cvt_pk_bf16_f32 v156, v126, v127
	v_cvt_pk_bf16_f32 v157, v122, v123
	v_lshl_add_u64 v[162:163], v[144:145], 1, v[162:163]
	global_store_dwordx4 v[162:163], v[154:157], off
	v_add_co_u32_e32 v162, vcc, 0x1000, v162
	s_nop 0
	v_cvt_pk_bf16_f32 v154, v184, v185
	v_cvt_pk_bf16_f32 v155, v160, v161
	v_cvt_pk_bf16_f32 v156, v128, v129
	v_cvt_pk_bf16_f32 v157, v124, v125
	v_addc_co_u32_e32 v163, vcc, 0, v163, vcc
	global_store_dwordx4 v[162:163], v[154:157], off offset:1536
.LBB0_797:
	s_or_b64 exec, exec, s[20:21]
	s_waitcnt lgkmcnt(0)
	v_mov_b32_e32 v154, v115
	v_mov_b32_e32 v155, v116
	v_mov_b32_e32 v115, v117
	v_mov_b32_e32 v116, v119
	v_mov_b32_e32 v117, v120
	v_mov_b32_e32 v119, v121
	v_pk_add_f32 v[114:115], v[154:155], v[114:115]
	v_pk_add_f32 v[116:117], v[116:117], v[118:119]
	v_mov_b32_e32 v119, v114
	v_mov_b32_e32 v118, v116
	v_mov_b32_e32 v114, v117
	v_pk_add_f32 v[114:115], v[118:119], v[114:115]
	s_mov_b32 s12, 0x3a800000
	v_pk_add_f32 v[114:115], v[114:115], 0 op_sel_hi:[1,0]
	s_nop 0
	v_pk_fma_f32 v[192:193], v[114:115], s[12:13], v[212:213] op_sel_hi:[1,0,0]
	s_nop 0
	v_mul_f32_e32 v114, 0x4b800000, v192
	v_cmp_gt_f32_e32 vcc, s69, v192
	v_cmp_gt_f32_e64 s[48:49], s69, v193
	s_nop 0
	v_cndmask_b32_e32 v114, v192, v114, vcc
	v_rsq_f32_e32 v114, v114
	s_nop 0
	v_mul_f32_e32 v115, 0x45800000, v114
	v_cndmask_b32_e32 v114, v114, v115, vcc
	v_pk_mul_f32 v[166:167], v[112:113], v[114:115] op_sel_hi:[1,0]
	v_pk_mul_f32 v[186:187], v[110:111], v[114:115] op_sel_hi:[1,0]
	v_pk_mul_f32 v[108:109], v[108:109], v[114:115] op_sel_hi:[1,0]
	v_pk_mul_f32 v[106:107], v[106:107], v[114:115] op_sel_hi:[1,0]
	v_pk_mul_f32 v[170:171], v[104:105], v[114:115] op_sel_hi:[1,0]
	v_pk_mul_f32 v[188:189], v[102:103], v[114:115] op_sel_hi:[1,0]
	v_pk_mul_f32 v[100:101], v[100:101], v[114:115] op_sel_hi:[1,0]
	v_pk_mul_f32 v[98:99], v[98:99], v[114:115] op_sel_hi:[1,0]
	s_and_saveexec_b64 s[20:21], s[40:41]
	s_cbranch_execz .LBB0_799
	v_lshl_add_u64 v[110:111], s[50:51], 0, v[138:139]
	v_mov_b64_e32 v[112:113], s[94:95]
	s_movk_i32 s12, 0x2c00
	v_mad_u64_u32 v[112:113], s[24:25], v110, s12, v[112:113]
	v_mad_i32_i24 v113, v111, s12, v113
	v_cvt_pk_bf16_f32 v102, v186, v187
	v_cvt_pk_bf16_f32 v103, v166, v167
	v_cvt_pk_bf16_f32 v104, v106, v107
	v_cvt_pk_bf16_f32 v105, v108, v109
	v_lshl_add_u64 v[110:111], v[144:145], 1, v[112:113]
	global_store_dwordx4 v[110:111], v[102:105], off
	v_add_co_u32_e32 v110, vcc, 0x1000, v110
	s_nop 0
	v_cvt_pk_bf16_f32 v102, v188, v189
	v_cvt_pk_bf16_f32 v103, v170, v171
	v_cvt_pk_bf16_f32 v104, v98, v99
	v_cvt_pk_bf16_f32 v105, v100, v101
	v_addc_co_u32_e32 v111, vcc, 0, v111, vcc
	global_store_dwordx4 v[110:111], v[102:105], off offset:1536
; __device__ __forceinline__ unsigned cvtpk(float lo, float hi) { f32x2 v = {lo, hi}; bf16x2_t b = __builtin_convertvector(v, bf16x2_t); return __builtin_bit_cast(unsigned, b); }
;     __device__ __forceinline__ void operator()(AccRef acc, const Unit& u, int wr, int wc, int fr, int fq) const {
;         const int row0 = u.pm * 256 + wr * 64 + fr, gcol = u.pn * 128 + wc * 32 + 8 * fq;
; #pragma unroll
;         for (int ai = 0; ai < 2; ++ai) {
; #pragma unroll
;             for (int m = 0; m < 4; ++m) {
;                 const float rs = rsqrtf(ssq_sum<4>(ssqx + (size_t)(row0 + ai * 128 + m * 16) * 4) * (1.0f / DM) + EPS);
; #pragma unroll
;                 for (int bj = 0; bj < 2; ++bj) { acc[ai][bj][m][0] = acc[ai][bj][m][0] * rs; acc[ai][bj][m][1] = acc[ai][bj][m][1] * rs; }
;             }
;             asm volatile("" ::: "memory");
;             const int chunk = u.pm * 4 + ai * 2 + wr;
; #pragma unroll
;             for (int e = 0; e < 2; ++e) {
;                 const int m = e ? 3 : 0;
;                 const bool mine = e ? (fr >= 14) : (fr <= 1);
;                 const int slot = e ? (fr - 12) : fr;
;                 if (mine) {
; #pragma unroll
;                     for (int bj = 0; bj < 2; ++bj) {
;                         const f32x4 v0 = acc[ai][bj][m][0], v1 = acc[ai][bj][m][1];
;                         u32x4 w; w.x = cvtpk(v0[0], v0[1]); w.y = cvtpk(v0[2], v0[3]); w.z = cvtpk(v1[0], v1[1]); w.w = cvtpk(v1[2], v1[3]);
;                         *(u32x4*)(UB + ((size_t)chunk * 4 + slot) * NUP + bj * DFF + gcol) = w;
;                     }
;                 }
;             }
.LBB0_799:
	s_or_b64 exec, exec, s[20:21]
	s_nop 0
	v_add_u32_e32 v102, 0x80, v146
	v_ashrrev_i32_e32 v103, 31, v102
	v_and_b32_e32 v104, 0xff, v102
	v_lshlrev_b32_e32 v104, 4, v104
	v_add_u32_e32 v104, 0x21400, v104
	ds_read_b128 v[110:113], v104
	s_mov_b32 s12, 0x3a800000
	s_add_i32 s52, s52, 2
	s_ashr_i32 s53, s52, 31
	s_lshl_b64 s[20:21], s[52:53], 2
	s_waitcnt lgkmcnt(0)
	v_mov_b32_e32 v104, v111
	v_mov_b32_e32 v105, v112
	v_mov_b32_e32 v111, v113
	v_pk_add_f32 v[114:115], v[104:105], v[110:111]
	v_add_u32_e32 v104, 0x90, v146
	v_ashrrev_i32_e32 v105, 31, v104
	v_and_b32_e32 v110, 0xff, v104
	v_lshlrev_b32_e32 v110, 4, v110
	v_add_u32_e32 v110, 0x21400, v110
	ds_read_b128 v[110:113], v110
	s_waitcnt lgkmcnt(0)
	v_mov_b32_e32 v116, v111
	v_mov_b32_e32 v117, v112
	v_mov_b32_e32 v111, v113
	v_pk_add_f32 v[110:111], v[116:117], v[110:111]
	v_mov_b32_e32 v113, v114
	v_mov_b32_e32 v112, v110
	v_mov_b32_e32 v114, v111
	v_pk_add_f32 v[110:111], v[112:113], v[114:115]
	v_add_u32_e32 v112, 0xb0, v146
	v_pk_add_f32 v[110:111], v[110:111], 0 op_sel_hi:[1,0]
	v_ashrrev_i32_e32 v113, 31, v112
	v_pk_fma_f32 v[118:119], v[110:111], s[12:13], v[212:213] op_sel_hi:[1,0,0]
	s_nop 0
	v_mul_f32_e32 v103, 0x4b800000, v119
	v_cmp_gt_f32_e32 vcc, s69, v119
	v_cmp_gt_f32_e64 s[50:51], s69, v118
	s_nop 0
	v_cndmask_b32_e32 v103, v119, v103, vcc
	v_rsq_f32_e32 v103, v103
	s_nop 0
	v_mul_f32_e32 v105, 0x45800000, v103
	v_cndmask_b32_e32 v110, v103, v105, vcc
	v_pk_mul_f32 v[114:115], v[96:97], v[110:111] op_sel_hi:[1,0]
	v_pk_mul_f32 v[162:163], v[94:95], v[110:111] op_sel_hi:[1,0]
	v_pk_mul_f32 v[92:93], v[92:93], v[110:111] op_sel_hi:[1,0]
	v_pk_mul_f32 v[94:95], v[90:91], v[110:111] op_sel_hi:[1,0]
	v_pk_mul_f32 v[116:117], v[88:89], v[110:111] op_sel_hi:[1,0]
	v_pk_mul_f32 v[164:165], v[86:87], v[110:111] op_sel_hi:[1,0]
	v_pk_mul_f32 v[90:91], v[84:85], v[110:111] op_sel_hi:[1,0]
	v_pk_mul_f32 v[96:97], v[82:83], v[110:111] op_sel_hi:[1,0]
	v_add_u32_e32 v110, 0xa0, v146
	v_ashrrev_i32_e32 v111, 31, v110
	v_and_b32_e32 v82, 0xff, v110
	v_lshlrev_b32_e32 v82, 4, v82
	v_add_u32_e32 v82, 0x21400, v82
	v_and_b32_e32 v86, 0xff, v112
	v_lshlrev_b32_e32 v86, 4, v86
	v_add_u32_e32 v86, 0x21400, v86
	ds_read_b128 v[82:85], v82
	s_nop 0
	ds_read_b128 v[86:89], v86
	s_and_saveexec_b64 s[52:53], s[42:43]
	s_cbranch_execz .LBB0_801
	v_or_b32_e32 v103, s20, v136
	v_mov_b64_e32 v[120:121], s[94:95]
	s_movk_i32 s12, 0x2c00
	v_mad_u64_u32 v[120:121], s[24:25], v103, s12, v[120:121]
	v_mad_i32_i24 v121, s21, v240, v121
	v_cvt_pk_bf16_f32 v154, v162, v163
	v_cvt_pk_bf16_f32 v155, v114, v115
	v_cvt_pk_bf16_f32 v156, v94, v95
	v_cvt_pk_bf16_f32 v157, v92, v93
	v_lshl_add_u64 v[120:121], v[144:145], 1, v[120:121]
	global_store_dwordx4 v[120:121], v[154:157], off
	v_add_co_u32_e32 v120, vcc, 0x1000, v120
	s_nop 0
	v_cvt_pk_bf16_f32 v154, v164, v165
	v_cvt_pk_bf16_f32 v155, v116, v117
	v_cvt_pk_bf16_f32 v156, v96, v97
	v_cvt_pk_bf16_f32 v157, v90, v91
	v_addc_co_u32_e32 v121, vcc, 0, v121, vcc
	global_store_dwordx4 v[120:121], v[154:157], off offset:1536
.LBB0_801:
	s_or_b64 exec, exec, s[52:53]
	s_waitcnt lgkmcnt(0)
	v_mov_b32_e32 v120, v83
	v_mov_b32_e32 v121, v84
	v_mov_b32_e32 v83, v85
	v_mov_b32_e32 v84, v87
	v_mov_b32_e32 v85, v88
	v_mov_b32_e32 v87, v89
	v_pk_add_f32 v[82:83], v[120:121], v[82:83]
	v_pk_add_f32 v[84:85], v[84:85], v[86:87]
	v_mov_b32_e32 v87, v82
	v_mov_b32_e32 v86, v84
	v_mov_b32_e32 v82, v85
	v_pk_add_f32 v[82:83], v[86:87], v[82:83]
	s_mov_b32 s12, 0x3a800000
	v_pk_add_f32 v[82:83], v[82:83], 0 op_sel_hi:[1,0]
	s_nop 0
	v_pk_fma_f32 v[84:85], v[82:83], s[12:13], v[212:213] op_sel_hi:[1,0,0]
	s_nop 0
	v_mul_f32_e32 v82, 0x4b800000, v84
	v_cmp_gt_f32_e32 vcc, s69, v84
	v_cmp_gt_f32_e64 s[52:53], s69, v85
	s_nop 0
	v_cndmask_b32_e32 v82, v84, v82, vcc
	v_rsq_f32_e32 v82, v82
	s_nop 0
	v_mul_f32_e32 v83, 0x45800000, v82
	v_cndmask_b32_e32 v84, v82, v83, vcc
	v_pk_mul_f32 v[80:81], v[80:81], v[84:85] op_sel_hi:[1,0]
	v_pk_mul_f32 v[168:169], v[78:79], v[84:85] op_sel_hi:[1,0]
	v_pk_mul_f32 v[76:77], v[76:77], v[84:85] op_sel_hi:[1,0]
	v_pk_mul_f32 v[74:75], v[74:75], v[84:85] op_sel_hi:[1,0]
	v_pk_mul_f32 v[82:83], v[72:73], v[84:85] op_sel_hi:[1,0]
	v_pk_mul_f32 v[172:173], v[70:71], v[84:85] op_sel_hi:[1,0]
	v_pk_mul_f32 v[68:69], v[68:69], v[84:85] op_sel_hi:[1,0]
	v_pk_mul_f32 v[66:67], v[66:67], v[84:85] op_sel_hi:[1,0]
	s_and_saveexec_b64 s[24:25], s[40:41]
	s_cbranch_execz .LBB0_803
	v_lshl_add_u64 v[78:79], s[20:21], 0, v[138:139]
	v_mov_b64_e32 v[86:87], s[94:95]
	s_movk_i32 s12, 0x2c00
	v_mad_u64_u32 v[86:87], s[20:21], v78, s12, v[86:87]
	v_mad_i32_i24 v87, v79, s12, v87
	v_cvt_pk_bf16_f32 v70, v168, v169
	v_cvt_pk_bf16_f32 v71, v80, v81
	v_cvt_pk_bf16_f32 v72, v74, v75
	v_cvt_pk_bf16_f32 v73, v76, v77
	v_lshl_add_u64 v[78:79], v[144:145], 1, v[86:87]
	global_store_dwordx4 v[78:79], v[70:73], off
	v_add_co_u32_e32 v78, vcc, 0x1000, v78
	s_nop 0
	v_cvt_pk_bf16_f32 v70, v172, v173
	v_cvt_pk_bf16_f32 v71, v82, v83
	v_cvt_pk_bf16_f32 v72, v66, v67
	v_cvt_pk_bf16_f32 v73, v68, v69
	v_addc_co_u32_e32 v79, vcc, 0, v79, vcc
	global_store_dwordx4 v[78:79], v[70:73], off offset:1536
